# attention steps: the four guarded K/V LDS-DMA issues per step merged into two guarded pairs (two scalar branches fewer in the MFMA stream per step), DMA order and vmcnt accounting unchanged
# baseline (speedup 1.0000x reference)
.LBB0_276:
	s_and_b64 vcc, exec, s[38:39]
	v_exp_f32_e32 v112, v112
	v_exp_f32_e32 v113, v113
	v_exp_f32_e32 v114, v114
	v_exp_f32_e32 v115, v115
	v_add_f32_e32 v80, v189, v112
	v_add_f32_e32 v81, v188, v113
	v_exp_f32_e32 v116, v116
	v_exp_f32_e32 v117, v117
	v_exp_f32_e32 v118, v118
	v_exp_f32_e32 v119, v119
	v_add_f32_e32 v80, v114, v80
	v_add_f32_e32 v81, v115, v81
	v_cvt_pk_bf16_f32 v188, v112, v113
	v_add_f32_e32 v80, v116, v80
	v_add_f32_e32 v81, v117, v81
	v_cvt_pk_bf16_f32 v189, v114, v115
	v_add_f32_e32 v100, v118, v80
	v_add_f32_e32 v101, v119, v81
	v_cvt_pk_bf16_f32 v190, v116, v117
	v_cvt_pk_bf16_f32 v191, v118, v119
	v_exp_f32_e32 v120, v120
	v_exp_f32_e32 v121, v121
	s_waitcnt lgkmcnt(6)
	v_mfma_f32_32x32x16_bf16 v[80:95], v[96:99], v[144:147], v[64:79]
	v_add_u32_e32 v96, v237, v226
	v_add_f32_e32 v194, v120, v100
	v_add_f32_e32 v195, v121, v101
	ds_read_b128 v[238:241], v96 offset:32768
	ds_read_b128 v[242:245], v96 offset:40960
	v_exp_f32_e32 v122, v122
	v_exp_f32_e32 v123, v123
	v_mfma_f32_32x32x16_bf16 v[96:111], v[184:187], v[144:147], v[64:79]
	v_add_u32_e32 v186, v237, v227
	v_add_f32_e32 v184, v122, v194
	v_add_f32_e32 v185, v123, v195
	ds_read_b128 v[246:249], v186 offset:32768
	ds_read_b128 v[250:253], v186 offset:40960
	s_waitcnt lgkmcnt(8)
	v_mfma_f32_32x32x16_bf16 v[80:95], v[180:183], v[148:151], v[80:95]
	v_exp_f32_e32 v124, v124
	v_exp_f32_e32 v125, v125
	v_add_f32_e32 v180, v124, v184
	v_add_f32_e32 v181, v125, v185
	s_cbranch_vccnz .Latt_dA0
	s_mov_b32 m0, s11
	s_nop 0
	global_load_lds_dwordx4 v206, s[98:99]
	s_add_i32 m0, s11, 0x4000
	s_nop 0
	global_load_lds_dwordx4 v202, s[100:101]
.Latt_dA0:
	v_mfma_f32_32x32x16_bf16 v[96:111], v[176:179], v[148:151], v[96:111]
	v_exp_f32_e32 v126, v126
	v_exp_f32_e32 v127, v127
	v_add_f32_e32 v237, v126, v180
	v_add_f32_e32 v219, v127, v181
	s_waitcnt lgkmcnt(2)
	v_mfma_f32_32x32x16_bf16 v[80:95], v[238:241], v[152:155], v[80:95]
	v_add_u32_e32 v180, v236, v230
	ds_read_b128 v[238:241], v180 offset:16384
	ds_read_b128 v[194:197], v180 offset:20480
	v_cvt_pk_bf16_f32 v176, v120, v121
	v_cvt_pk_bf16_f32 v177, v122, v123
	v_mfma_f32_32x32x16_bf16 v[96:111], v[242:245], v[152:155], v[96:111]
	ds_read_b128 v[184:187], v180 offset:24576
	ds_read_b128 v[180:183], v180 offset:28672
	v_cvt_pk_bf16_f32 v178, v124, v125
	v_cvt_pk_bf16_f32 v179, v126, v127
	s_waitcnt lgkmcnt(4)
	v_mfma_f32_32x32x16_bf16 v[80:95], v[246:249], v[156:159], v[80:95]
	v_exp_f32_e32 v128, v128
	v_exp_f32_e32 v129, v129
	v_add_f32_e32 v237, v128, v237
	v_add_f32_e32 v219, v129, v219
	s_cbranch_vccnz .Latt_dA2
	s_add_i32 m0, s11, 0x2000
	s_nop 0
	global_load_lds_dwordx4 v204, s[98:99]
	s_add_u32 s98, s98, 0x10000
	s_addc_u32 s99, s99, 0
	s_add_i32 m0, s11, 0x6000
	s_nop 0
	global_load_lds_dwordx4 v200, s[100:101]
	s_add_u32 s100, s100, 0x80
	s_addc_u32 s101, s101, 0
.Latt_dA2:
	v_mfma_f32_32x32x16_bf16 v[96:111], v[250:253], v[156:159], v[96:111]
	v_exp_f32_e32 v130, v130
	v_exp_f32_e32 v131, v131
	v_add_f32_e32 v237, v130, v237
	v_add_f32_e32 v219, v131, v219
	v_mfma_f32_32x32x16_bf16 v[48:63], v[172:175], v[188:191], v[48:63]
	v_exp_f32_e32 v132, v132
	v_exp_f32_e32 v133, v133
	v_add_f32_e32 v172, v132, v237
	v_add_f32_e32 v173, v133, v219
	v_mfma_f32_32x32x16_bf16 v[32:47], v[168:171], v[188:191], v[32:47]
	v_exp_f32_e32 v134, v134
	v_exp_f32_e32 v135, v135
	v_add_f32_e32 v168, v134, v172
	v_add_f32_e32 v169, v135, v173
	v_mfma_f32_32x32x16_bf16 v[0:15], v[164:167], v[188:191], v[0:15]
	v_exp_f32_e32 v136, v136
	v_exp_f32_e32 v137, v137
	v_cvt_pk_bf16_f32 v164, v128, v129
	v_cvt_pk_bf16_f32 v165, v130, v131
	v_add_f32_e32 v166, v136, v168
	v_add_f32_e32 v167, v137, v169
	v_mfma_f32_32x32x16_bf16 v[16:31], v[160:163], v[188:191], v[16:31]
	v_exp_f32_e32 v138, v138
	v_exp_f32_e32 v139, v139
	v_add_f32_e32 v160, v138, v166
	v_add_f32_e32 v161, v139, v167
	v_cvt_pk_bf16_f32 v166, v132, v133
	v_cvt_pk_bf16_f32 v167, v134, v135
	v_exp_f32_e32 v140, v140
	v_exp_f32_e32 v141, v141
	s_waitcnt lgkmcnt(0)
	v_mfma_f32_32x32x16_bf16 v[48:63], v[238:241], v[176:179], v[48:63]
	v_add_u32_e32 v190, v236, v231
	v_add_f32_e32 v172, v140, v160
	v_add_f32_e32 v173, v141, v161
	ds_read_b128 v[160:163], v190 offset:16384
	ds_read_b128 v[168:171], v190 offset:20480
	v_exp_f32_e32 v142, v142
	v_exp_f32_e32 v143, v143
	v_mfma_f32_32x32x16_bf16 v[32:47], v[194:197], v[176:179], v[32:47]
	v_add_f32_e32 v189, v142, v172
	v_add_f32_e32 v188, v143, v173
	ds_read_b128 v[172:175], v190 offset:24576
	ds_read_b128 v[194:197], v190 offset:28672
	v_mfma_f32_32x32x16_bf16 v[0:15], v[184:187], v[176:179], v[0:15]
	v_cvt_pk_bf16_f32 v184, v136, v137
	v_cvt_pk_bf16_f32 v185, v138, v139
	v_mfma_f32_32x32x16_bf16 v[16:31], v[180:183], v[176:179], v[16:31]
	v_cvt_pk_bf16_f32 v186, v140, v141
	v_cvt_pk_bf16_f32 v187, v142, v143
	s_waitcnt lgkmcnt(0)
	v_mfma_f32_32x32x16_bf16 v[48:63], v[160:163], v[164:167], v[48:63]
	v_add_u32_e32 v180, v236, v232
	ds_read_b128 v[160:163], v180 offset:16384
	ds_read_b128 v[176:179], v180 offset:20480
	v_max_f32_e32 v190, v80, v96
	v_max3_f32 v191, v97, v82, v98
	v_mfma_f32_32x32x16_bf16 v[32:47], v[168:171], v[164:167], v[32:47]
	ds_read_b128 v[168:171], v180 offset:24576
	ds_read_b128 v[180:183], v180 offset:28672
	v_max3_f32 v190, v190, v81, v83
	v_max3_f32 v191, v191, v84, v100
	v_mfma_f32_32x32x16_bf16 v[0:15], v[172:175], v[164:167], v[0:15]
	v_max3_f32 v172, v190, v99, v85
	v_max3_f32 v173, v191, v86, v102
	v_mfma_f32_32x32x16_bf16 v[16:31], v[194:197], v[164:167], v[16:31]
	v_max3_f32 v164, v172, v101, v87
	v_max3_f32 v165, v173, v88, v104
	s_waitcnt lgkmcnt(0)
	v_mfma_f32_32x32x16_bf16 v[48:63], v[160:163], v[184:187], v[48:63]
	v_max3_f32 v160, v164, v103, v89
	v_max3_f32 v161, v165, v90, v106
	v_mfma_f32_32x32x16_bf16 v[32:47], v[176:179], v[184:187], v[32:47]
	v_max3_f32 v160, v160, v105, v91
	v_max3_f32 v161, v161, v92, v108
	v_mfma_f32_32x32x16_bf16 v[0:15], v[168:171], v[184:187], v[0:15]
	v_max3_f32 v160, v160, v107, v93
	v_max3_f32 v161, v161, v94, v110
	v_mfma_f32_32x32x16_bf16 v[16:31], v[180:183], v[184:187], v[16:31]
	v_max3_f32 v160, v160, v109, v95
	v_max3_f32 v190, v160, v111, v161
	s_mov_b64 s[80:81], -1
	s_and_b64 vcc, exec, s[38:39]
	s_cbranch_vccnz .LBB0_277
	s_add_i32 s10, s96, 6
	s_cmp_le_u32 s10, s94
	s_cselect_b64 s[38:39], -1, 0
	s_cmp_ge_u32 s45, s95
	s_waitcnt vmcnt(4) lgkmcnt(0)
	s_barrier
	s_cbranch_scc1 .LBB0_268

.LBB0_281:
	s_andn2_b64 vcc, exec, s[38:39]
	v_exp_f32_e32 v80, v80
	v_exp_f32_e32 v81, v81
	v_exp_f32_e32 v82, v82
	v_exp_f32_e32 v83, v83
	v_add_f32_e32 v112, v189, v80
	v_add_f32_e32 v113, v188, v81
	v_exp_f32_e32 v84, v84
	v_exp_f32_e32 v85, v85
	v_exp_f32_e32 v86, v86
	v_exp_f32_e32 v87, v87
	v_add_f32_e32 v112, v82, v112
	v_add_f32_e32 v113, v83, v113
	v_cvt_pk_bf16_f32 v188, v80, v81
	v_add_f32_e32 v112, v84, v112
	v_add_f32_e32 v113, v85, v113
	v_cvt_pk_bf16_f32 v189, v82, v83
	v_add_f32_e32 v132, v86, v112
	v_add_f32_e32 v133, v87, v113
	v_cvt_pk_bf16_f32 v190, v84, v85
	v_cvt_pk_bf16_f32 v191, v86, v87
	v_exp_f32_e32 v88, v88
	v_exp_f32_e32 v89, v89
	s_waitcnt lgkmcnt(6)
	v_mfma_f32_32x32x16_bf16 v[112:127], v[128:131], v[144:147], v[64:79]
	v_add_u32_e32 v128, v209, v226
	v_add_f32_e32 v214, v88, v132
	v_add_f32_e32 v215, v89, v133
	ds_read_b128 v[194:197], v128
	ds_read_b128 v[210:213], v128 offset:8192
	v_exp_f32_e32 v90, v90
	v_exp_f32_e32 v91, v91
	v_mfma_f32_32x32x16_bf16 v[128:143], v[184:187], v[144:147], v[64:79]
	v_add_u32_e32 v186, v209, v227
	v_add_f32_e32 v184, v90, v214
	v_add_f32_e32 v185, v91, v215
	ds_read_b128 v[236:239], v186
	ds_read_b128 v[240:243], v186 offset:8192
	s_waitcnt lgkmcnt(8)
	v_mfma_f32_32x32x16_bf16 v[112:127], v[180:183], v[148:151], v[112:127]
	v_exp_f32_e32 v92, v92
	v_exp_f32_e32 v93, v93
	v_add_f32_e32 v180, v92, v184
	v_add_f32_e32 v181, v93, v185
	s_cbranch_vccnz .Latt_dB0
	s_mov_b32 m0, s10
	s_nop 0
	global_load_lds_dwordx4 v206, s[98:99]
	s_add_i32 m0, s10, 0x4000
	s_nop 0
	global_load_lds_dwordx4 v202, s[100:101]
.Latt_dB0:
	v_mfma_f32_32x32x16_bf16 v[128:143], v[176:179], v[148:151], v[128:143]
	v_exp_f32_e32 v94, v94
	v_exp_f32_e32 v95, v95
	v_add_f32_e32 v209, v94, v180
	v_add_f32_e32 v214, v95, v181
	s_waitcnt lgkmcnt(2)
	v_mfma_f32_32x32x16_bf16 v[112:127], v[194:197], v[152:155], v[112:127]
	v_add_u32_e32 v180, v208, v230
	ds_read_b128 v[194:197], v180 offset:49152
	ds_read_b128 v[244:247], v180 offset:53248
	v_cvt_pk_bf16_f32 v176, v88, v89
	v_cvt_pk_bf16_f32 v177, v90, v91
	v_mfma_f32_32x32x16_bf16 v[128:143], v[210:213], v[152:155], v[128:143]
	ds_read_b128 v[184:187], v180 offset:57344
	ds_read_b128 v[180:183], v180 offset:61440
	v_cvt_pk_bf16_f32 v178, v92, v93
	v_cvt_pk_bf16_f32 v179, v94, v95
	s_waitcnt lgkmcnt(4)
	v_mfma_f32_32x32x16_bf16 v[112:127], v[236:239], v[156:159], v[112:127]
	v_exp_f32_e32 v96, v96
	v_exp_f32_e32 v97, v97
	v_add_f32_e32 v209, v96, v209
	v_add_f32_e32 v210, v97, v214
	s_cbranch_vccnz .Latt_dB2
	s_add_i32 m0, s10, 0x2000
	s_nop 0
	global_load_lds_dwordx4 v204, s[98:99]
	s_add_u32 s98, s98, 0x10000
	s_addc_u32 s99, s99, 0
	s_add_i32 m0, s10, 0x6000
	s_nop 0
	global_load_lds_dwordx4 v200, s[100:101]
	s_add_u32 s100, s100, 0x80
	s_addc_u32 s101, s101, 0
.Latt_dB2:
	v_mfma_f32_32x32x16_bf16 v[128:143], v[240:243], v[156:159], v[128:143]
	v_exp_f32_e32 v98, v98
	v_exp_f32_e32 v99, v99
	v_add_f32_e32 v209, v98, v209
	v_add_f32_e32 v210, v99, v210
	v_mfma_f32_32x32x16_bf16 v[48:63], v[172:175], v[188:191], v[48:63]
	v_exp_f32_e32 v100, v100
	v_exp_f32_e32 v101, v101
	v_add_f32_e32 v172, v100, v209
	v_add_f32_e32 v173, v101, v210
	v_mfma_f32_32x32x16_bf16 v[32:47], v[168:171], v[188:191], v[32:47]
	v_exp_f32_e32 v102, v102
	v_exp_f32_e32 v103, v103
	v_add_f32_e32 v168, v102, v172
	v_add_f32_e32 v169, v103, v173
	v_mfma_f32_32x32x16_bf16 v[0:15], v[164:167], v[188:191], v[0:15]
	v_exp_f32_e32 v104, v104
	v_exp_f32_e32 v105, v105
	v_cvt_pk_bf16_f32 v164, v96, v97
	v_cvt_pk_bf16_f32 v165, v98, v99
	v_add_f32_e32 v166, v104, v168
	v_add_f32_e32 v167, v105, v169
	v_mfma_f32_32x32x16_bf16 v[16:31], v[160:163], v[188:191], v[16:31]
	v_exp_f32_e32 v106, v106
	v_exp_f32_e32 v107, v107
	v_add_f32_e32 v160, v106, v166
	v_add_f32_e32 v161, v107, v167
	v_cvt_pk_bf16_f32 v166, v100, v101
	v_cvt_pk_bf16_f32 v167, v102, v103
	v_exp_f32_e32 v108, v108
	v_exp_f32_e32 v109, v109
	s_waitcnt lgkmcnt(0)
	v_mfma_f32_32x32x16_bf16 v[48:63], v[194:197], v[176:179], v[48:63]
	v_add_u32_e32 v190, v208, v231
	v_add_f32_e32 v172, v108, v160
	v_add_f32_e32 v173, v109, v161
	ds_read_b128 v[160:163], v190 offset:49152
	ds_read_b128 v[168:171], v190 offset:53248
	v_exp_f32_e32 v110, v110
	v_exp_f32_e32 v111, v111
	v_mfma_f32_32x32x16_bf16 v[32:47], v[244:247], v[176:179], v[32:47]
	v_add_f32_e32 v189, v110, v172
	v_add_f32_e32 v188, v111, v173
	ds_read_b128 v[172:175], v190 offset:57344
	ds_read_b128 v[194:197], v190 offset:61440
	v_mfma_f32_32x32x16_bf16 v[0:15], v[184:187], v[176:179], v[0:15]
	v_cvt_pk_bf16_f32 v184, v104, v105
	v_cvt_pk_bf16_f32 v185, v106, v107
	v_mfma_f32_32x32x16_bf16 v[16:31], v[180:183], v[176:179], v[16:31]
	v_cvt_pk_bf16_f32 v186, v108, v109
	v_cvt_pk_bf16_f32 v187, v110, v111
	s_waitcnt lgkmcnt(0)
	v_mfma_f32_32x32x16_bf16 v[48:63], v[160:163], v[164:167], v[48:63]
	v_add_u32_e32 v180, v208, v232
	ds_read_b128 v[160:163], v180 offset:49152
	ds_read_b128 v[176:179], v180 offset:53248
	v_max_f32_e32 v190, v112, v128
	v_max3_f32 v191, v129, v114, v130
	v_mfma_f32_32x32x16_bf16 v[32:47], v[168:171], v[164:167], v[32:47]
	ds_read_b128 v[168:171], v180 offset:57344
	ds_read_b128 v[180:183], v180 offset:61440
	v_max3_f32 v190, v190, v113, v115
	v_max3_f32 v191, v191, v116, v132
	v_mfma_f32_32x32x16_bf16 v[0:15], v[172:175], v[164:167], v[0:15]
	v_max3_f32 v172, v190, v131, v117
	v_max3_f32 v173, v191, v118, v134
	v_mfma_f32_32x32x16_bf16 v[16:31], v[194:197], v[164:167], v[16:31]
	v_max3_f32 v164, v172, v133, v119
	v_max3_f32 v165, v173, v120, v136
	s_waitcnt lgkmcnt(0)
	v_mfma_f32_32x32x16_bf16 v[48:63], v[160:163], v[184:187], v[48:63]
	v_max3_f32 v160, v164, v135, v121
	v_max3_f32 v161, v165, v122, v138
	v_mfma_f32_32x32x16_bf16 v[32:47], v[176:179], v[184:187], v[32:47]
	v_max3_f32 v160, v160, v137, v123
	v_max3_f32 v161, v161, v124, v140
	v_mfma_f32_32x32x16_bf16 v[0:15], v[168:171], v[184:187], v[0:15]
	v_max3_f32 v160, v160, v139, v125
	v_max3_f32 v161, v161, v126, v142
	v_mfma_f32_32x32x16_bf16 v[16:31], v[180:183], v[184:187], v[16:31]
	v_max3_f32 v160, v160, v141, v127
	v_max3_f32 v190, v160, v143, v161
	s_andn2_b64 vcc, exec, s[38:39]
	s_mov_b64 s[38:39], -1
	s_cbranch_vccnz .LBB0_269
